# P1 K-loop regenerated: saddr-form LDS-DMA (no VALU address math), DMAs issued before ds_reads in each load segment
# baseline (speedup 1.0000x reference)
; #define PG8_STAGE(bufoff, gbase, voff) do { _Pragma("unroll") for (int _i = 0; _i < 2; ++_i) \
;         __builtin_amdgcn_global_load_lds((const unsigned*)((const char*)(gbase) + (voff)[_i]), (PG8_LAS unsigned*)(lds + (bufoff) + ldsw + _i * 8192), 16, 0, 0); } while (0)
; #define PG8_LDA(dst, b, h) do { _Pragma("unroll") for (int m = 0; m < 4; ++m) _Pragma("unroll") for (int k = 0; k < 2; ++k) dst[m][k] = *(const PG8_LAS bf16x8*)(lds + PG8_SA(b, h) + aoff + m * 2048 + k * 1024); } while (0)
; #define PG8_LDB(dst, b, h) do { _Pragma("unroll") for (int n = 0; n < 2; ++n) _Pragma("unroll") for (int k = 0; k < 2; ++k) dst[n][k] = *(const PG8_LAS bf16x8*)(lds + PG8_SB(b, h) + boff + n * 2048 + k * 1024); } while (0)
; #define PG8_MMA(ai, bj, At, Bt) do { __builtin_amdgcn_s_setprio(1); _Pragma("unroll") for (int m = 0; m < 4; ++m) _Pragma("unroll") for (int n = 0; n < 2; ++n) _Pragma("unroll") for (int k = 0; k < 2; ++k) \
;         acc[ai][bj][m][n] = __builtin_amdgcn_mfma_f32_16x16x32_bf16(Bt[n][k], At[m][k], acc[ai][bj][m][n], 0, 0, 0); __builtin_amdgcn_s_setprio(0); } while (0)
; #define PG8_BAR __builtin_amdgcn_s_barrier()
; template <class Epi, class Sched>
; __device__ __forceinline__ void gemm_phase(PG8_LAS unsigned char* lds, const Gemm g, const Sched& S, const Epi& E) {
;     ...
;     for (;;) {
;         const bool has_next = S.next(ui + 1, nxt);
;         const char* nA = has_next ? (const char*)nxt.A : cA; const char* nB = has_next ? (const char*)nxt.B : cB;
;         for (int t = 0; t < nt; t += 2) {
;             const bool last = (t == nt - 2);
;             const char* a1 = cA + (size_t)(t + 1) * kstep;
;             const char* a2 = last ? nA : cA + (size_t)(t + 2) * kstep; const char* b2 = last ? nB : cB + (size_t)(t + 2) * kstep;
;             const char* a3 = a2 + kstep; const char* b3 = b2 + kstep;
;             PG8_LDB(B0, 0, 0); PG8_LDB(B1, 0, 1); PG8_SCHED; PG8_LDA(At, 0, 0); PG8_STAGE(PG8_SA(1, 1), a1 + hstepA, voffA);
;             PG8_WAIT_V(8); PG8_WAIT_L(0); PG8_BAR; PG8_MMA(0, 0, At, B0); PG8_MMA(0, 1, At, B1); PG8_BAR; PG8_SCHED;
;     ...
; #pragma unroll
;         for (int a = 0; a < 2; ++a)
; #pragma unroll
;             for (int b = 0; b < 2; ++b)
; #pragma unroll
;                 for (int m = 0; m < 4; ++m)
; #pragma unroll
;                     for (int n = 0; n < 2; ++n) acc[a][b][m][n] = (f32x4){0.f, 0.f, 0.f, 0.f};
.LBB0_160:
	s_add_u32 s6, s6, 0x40080
	s_addc_u32 s7, s7, 0
	s_add_u32 s2, s52, 0x100
	v_mov_b32_e32 v2, 0
	s_addc_u32 s18, s53, 0
	s_mov_b32 s39, -2
	v_mov_b32_e32 v3, v2
	v_mov_b32_e32 v4, v2
	v_mov_b32_e32 v5, v2
	v_mov_b32_e32 v6, v2
	v_mov_b32_e32 v7, v2
	v_mov_b32_e32 v8, v2
	v_mov_b32_e32 v9, v2
	v_mov_b32_e32 v10, v2
	v_mov_b32_e32 v11, v2
	v_mov_b32_e32 v12, v2
	v_mov_b32_e32 v13, v2
	v_mov_b32_e32 v14, v2
	v_mov_b32_e32 v15, v2
	v_mov_b32_e32 v16, v2
	v_mov_b32_e32 v17, v2
	v_mov_b32_e32 v18, v2
	v_mov_b32_e32 v19, v2
	v_mov_b32_e32 v20, v2
	v_mov_b32_e32 v21, v2
	v_mov_b32_e32 v22, v2
	v_mov_b32_e32 v23, v2
	v_mov_b32_e32 v24, v2
	v_mov_b32_e32 v25, v2
	v_mov_b32_e32 v26, v2
	v_mov_b32_e32 v27, v2
	v_mov_b32_e32 v28, v2
	v_mov_b32_e32 v29, v2
	v_mov_b32_e32 v30, v2
	v_mov_b32_e32 v31, v2
	v_mov_b32_e32 v32, v2
	v_mov_b32_e32 v33, v2
	v_mov_b32_e32 v66, v2
	v_mov_b32_e32 v67, v2
	v_mov_b32_e32 v68, v2
	v_mov_b32_e32 v69, v2
	v_mov_b32_e32 v70, v2
	v_mov_b32_e32 v71, v2
	v_mov_b32_e32 v72, v2
	v_mov_b32_e32 v73, v2
	v_mov_b32_e32 v74, v2
	v_mov_b32_e32 v75, v2
	v_mov_b32_e32 v76, v2
	v_mov_b32_e32 v77, v2
	v_mov_b32_e32 v78, v2
	v_mov_b32_e32 v79, v2
	v_mov_b32_e32 v80, v2
	v_mov_b32_e32 v81, v2
	v_mov_b32_e32 v82, v2
	v_mov_b32_e32 v83, v2
	v_mov_b32_e32 v84, v2
	v_mov_b32_e32 v85, v2
	v_mov_b32_e32 v86, v2
	v_mov_b32_e32 v87, v2
	v_mov_b32_e32 v88, v2
	v_mov_b32_e32 v89, v2
	v_mov_b32_e32 v90, v2
	v_mov_b32_e32 v91, v2
	v_mov_b32_e32 v92, v2
	v_mov_b32_e32 v93, v2
	v_mov_b32_e32 v94, v2
	v_mov_b32_e32 v95, v2
	v_mov_b32_e32 v96, v2
	v_mov_b32_e32 v97, v2
	v_mov_b32_e32 v34, v2
	v_mov_b32_e32 v35, v2
	v_mov_b32_e32 v36, v2
	v_mov_b32_e32 v37, v2
	v_mov_b32_e32 v38, v2
	v_mov_b32_e32 v39, v2
	v_mov_b32_e32 v40, v2
	v_mov_b32_e32 v41, v2
	v_mov_b32_e32 v42, v2
	v_mov_b32_e32 v43, v2
	v_mov_b32_e32 v44, v2
	v_mov_b32_e32 v45, v2
	v_mov_b32_e32 v46, v2
	v_mov_b32_e32 v47, v2
	v_mov_b32_e32 v48, v2
	v_mov_b32_e32 v49, v2
	v_mov_b32_e32 v50, v2
	v_mov_b32_e32 v51, v2
	v_mov_b32_e32 v52, v2
	v_mov_b32_e32 v53, v2
	v_mov_b32_e32 v54, v2
	v_mov_b32_e32 v55, v2
	v_mov_b32_e32 v56, v2
	v_mov_b32_e32 v57, v2
	v_mov_b32_e32 v58, v2
	v_mov_b32_e32 v59, v2
	v_mov_b32_e32 v60, v2
	v_mov_b32_e32 v61, v2
	v_mov_b32_e32 v62, v2
	v_mov_b32_e32 v63, v2
	v_mov_b32_e32 v64, v2
	v_mov_b32_e32 v65, v2
	v_mov_b32_e32 v98, v2
	v_mov_b32_e32 v99, v2
	v_mov_b32_e32 v100, v2
	v_mov_b32_e32 v101, v2
	v_mov_b32_e32 v102, v2
	v_mov_b32_e32 v103, v2
	v_mov_b32_e32 v104, v2
	v_mov_b32_e32 v105, v2
	v_mov_b32_e32 v106, v2
	v_mov_b32_e32 v107, v2
	v_mov_b32_e32 v108, v2
	v_mov_b32_e32 v109, v2
	v_mov_b32_e32 v110, v2
	v_mov_b32_e32 v111, v2
	v_mov_b32_e32 v112, v2
	v_mov_b32_e32 v113, v2
	v_mov_b32_e32 v114, v2
	v_mov_b32_e32 v115, v2
	v_mov_b32_e32 v116, v2
	v_mov_b32_e32 v117, v2
	v_mov_b32_e32 v118, v2
	v_mov_b32_e32 v119, v2
	v_mov_b32_e32 v120, v2
	v_mov_b32_e32 v121, v2
	v_mov_b32_e32 v122, v2
	v_mov_b32_e32 v123, v2
	v_mov_b32_e32 v124, v2
	v_mov_b32_e32 v125, v2
	v_mov_b32_e32 v126, v2
	v_mov_b32_e32 v127, v2
	v_mov_b32_e32 v128, v2
	v_mov_b32_e32 v129, v2
	.LBB0_161:
	s_add_u32 s41, s6, 0xfffc0080
	s_addc_u32 s49, s7, -1
	s_cmp_eq_u32 s39, 12
	s_cselect_b32 s55, s43, s49
	s_cselect_b32 s54, s42, s41
	s_cselect_b32 s53, s45, s18
	s_cselect_b32 s52, s44, s2
	s_add_i32 m0, s60, 0xc000
	s_add_i32 s57, 0, 0x10000
	global_load_lds_dwordx4 v146, s[6:7]
	s_add_i32 m0, s60, 0xe000
	s_add_i32 s41, 0, 0x14000
	global_load_lds_dwordx4 v148, s[6:7]
	v_add_u32_e32 v142, s57, v168
	v_add_u32_e32 v164, s41, v168
	ds_read_b128 v[130:133], v142
	ds_read_b128 v[134:137], v142 offset:1024
	ds_read_b128 v[138:141], v142 offset:2048
	ds_read_b128 v[142:145], v142 offset:3072
	ds_read_b128 v[156:159], v164
	ds_read_b128 v[160:163], v164 offset:1024
	ds_read_b128 v[170:173], v164 offset:2048
	ds_read_b128 v[174:177], v164 offset:3072
	ds_read_b128 v[178:181], v169
	ds_read_b128 v[182:185], v169 offset:1024
	ds_read_b128 v[186:189], v169 offset:2048
	ds_read_b128 v[190:193], v169 offset:3072
	ds_read_b128 v[202:205], v169 offset:4096
	ds_read_b128 v[206:209], v169 offset:5120
	ds_read_b128 v[210:213], v169 offset:6144
	ds_read_b128 v[214:217], v169 offset:7168
	s_waitcnt vmcnt(8)
	s_waitcnt lgkmcnt(0)
	s_barrier
	s_setprio 1
	s_waitcnt lgkmcnt(0)
	v_mfma_f32_16x16x32_bf16 v[126:129], v[130:133], v[178:181], v[126:129]
	v_mfma_f32_16x16x32_bf16 v[122:125], v[138:141], v[178:181], v[122:125]
	v_mfma_f32_16x16x32_bf16 v[118:121], v[130:133], v[186:189], v[118:121]
	v_mfma_f32_16x16x32_bf16 v[114:117], v[138:141], v[186:189], v[114:117]
	v_mfma_f32_16x16x32_bf16 v[110:113], v[130:133], v[202:205], v[110:113]
	v_mfma_f32_16x16x32_bf16 v[106:109], v[138:141], v[202:205], v[106:109]
	v_mfma_f32_16x16x32_bf16 v[102:105], v[130:133], v[210:213], v[102:105]
	v_mfma_f32_16x16x32_bf16 v[98:101], v[138:141], v[210:213], v[98:101]
	v_mfma_f32_16x16x32_bf16 v[126:129], v[134:137], v[182:185], v[126:129]
	v_mfma_f32_16x16x32_bf16 v[122:125], v[142:145], v[182:185], v[122:125]
	v_mfma_f32_16x16x32_bf16 v[118:121], v[134:137], v[190:193], v[118:121]
	v_mfma_f32_16x16x32_bf16 v[114:117], v[142:145], v[190:193], v[114:117]
	v_mfma_f32_16x16x32_bf16 v[110:113], v[134:137], v[206:209], v[110:113]
	v_mfma_f32_16x16x32_bf16 v[106:109], v[142:145], v[206:209], v[106:109]
	v_mfma_f32_16x16x32_bf16 v[102:105], v[134:137], v[214:217], v[102:105]
	v_mfma_f32_16x16x32_bf16 v[98:101], v[142:145], v[214:217], v[98:101]
	s_setprio 0
	s_setprio 1
	v_mfma_f32_16x16x32_bf16 v[62:65], v[156:159], v[178:181], v[62:65]
	v_mfma_f32_16x16x32_bf16 v[58:61], v[170:173], v[178:181], v[58:61]
	v_mfma_f32_16x16x32_bf16 v[54:57], v[156:159], v[186:189], v[54:57]
	v_mfma_f32_16x16x32_bf16 v[50:53], v[170:173], v[186:189], v[50:53]
	v_mfma_f32_16x16x32_bf16 v[46:49], v[156:159], v[202:205], v[46:49]
	v_mfma_f32_16x16x32_bf16 v[42:45], v[170:173], v[202:205], v[42:45]
	v_mfma_f32_16x16x32_bf16 v[38:41], v[156:159], v[210:213], v[38:41]
	v_mfma_f32_16x16x32_bf16 v[34:37], v[170:173], v[210:213], v[34:37]
	v_mfma_f32_16x16x32_bf16 v[62:65], v[160:163], v[182:185], v[62:65]
	v_mfma_f32_16x16x32_bf16 v[58:61], v[174:177], v[182:185], v[58:61]
	v_mfma_f32_16x16x32_bf16 v[54:57], v[160:163], v[190:193], v[54:57]
	v_mfma_f32_16x16x32_bf16 v[50:53], v[174:177], v[190:193], v[50:53]
	v_mfma_f32_16x16x32_bf16 v[46:49], v[160:163], v[206:209], v[46:49]
	v_mfma_f32_16x16x32_bf16 v[42:45], v[174:177], v[206:209], v[42:45]
	v_mfma_f32_16x16x32_bf16 v[38:41], v[160:163], v[214:217], v[38:41]
	v_mfma_f32_16x16x32_bf16 v[34:37], v[174:177], v[214:217], v[34:37]
	s_setprio 0
	s_barrier
; #define PG8_STAGE(bufoff, gbase, voff) do { _Pragma("unroll") for (int _i = 0; _i < 2; ++_i) \
;         __builtin_amdgcn_global_load_lds((const unsigned*)((const char*)(gbase) + (voff)[_i]), (PG8_LAS unsigned*)(lds + (bufoff) + ldsw + _i * 8192), 16, 0, 0); } while (0)
; #define PG8_LDA(dst, b, h) do { _Pragma("unroll") for (int m = 0; m < 4; ++m) _Pragma("unroll") for (int k = 0; k < 2; ++k) dst[m][k] = *(const PG8_LAS bf16x8*)(lds + PG8_SA(b, h) + aoff + m * 2048 + k * 1024); } while (0)
; #define PG8_LDB(dst, b, h) do { _Pragma("unroll") for (int n = 0; n < 2; ++n) _Pragma("unroll") for (int k = 0; k < 2; ++k) dst[n][k] = *(const PG8_LAS bf16x8*)(lds + PG8_SB(b, h) + boff + n * 2048 + k * 1024); } while (0)
; #define PG8_MMA(ai, bj, At, Bt) do { __builtin_amdgcn_s_setprio(1); _Pragma("unroll") for (int m = 0; m < 4; ++m) _Pragma("unroll") for (int n = 0; n < 2; ++n) _Pragma("unroll") for (int k = 0; k < 2; ++k) \
;         acc[ai][bj][m][n] = __builtin_amdgcn_mfma_f32_16x16x32_bf16(Bt[n][k], At[m][k], acc[ai][bj][m][n], 0, 0, 0); __builtin_amdgcn_s_setprio(0); } while (0)
; #define PG8_WAIT_V(n) asm volatile("s_waitcnt vmcnt(" #n ")" ::: "memory")
; #define PG8_WAIT_L(n) asm volatile("s_waitcnt lgkmcnt(" #n ")" ::: "memory")
; #define PG8_BAR __builtin_amdgcn_s_barrier()
; #define PG8_SCHED __builtin_amdgcn_sched_barrier(0)
; template <class Epi, class Sched>
; __device__ __forceinline__ void gemm_phase(PG8_LAS unsigned char* lds, const Gemm g, const Sched& S, const Epi& E) {
;     ...
;             PG8_LDA(At, 0, 1); PG8_STAGE(PG8_SB(0, 0), b2, voffB); PG8_STAGE(PG8_SB(0, 1), b2 + hstepB, voffB); PG8_STAGE(PG8_SA(0, 0), a2, voffA);
;             PG8_WAIT_V(8); PG8_WAIT_L(0); PG8_BAR; PG8_MMA(1, 0, At, B0); PG8_MMA(1, 1, At, B1); PG8_BAR; PG8_SCHED;
;             PG8_LDB(B0, 1, 0); PG8_LDB(B1, 1, 1); PG8_SCHED; PG8_LDA(At, 1, 0); PG8_STAGE(PG8_SA(0, 1), a2 + hstepA, voffA);
;             PG8_WAIT_V(8); PG8_WAIT_L(0); PG8_BAR; PG8_MMA(0, 0, At, B0); PG8_MMA(0, 1, At, B1); PG8_BAR; PG8_SCHED;
	s_add_i32 s49, s57, s59
	s_mov_b32 m0, s49
	s_add_u32 s74, s52, 0x10000
	s_addc_u32 s75, s53, 0
	global_load_lds_dwordx4 v0, s[52:53]
	s_add_i32 m0, s49, 0x2000
	s_nop 0
	global_load_lds_dwordx4 v150, s[52:53]
	s_add_i32 s41, s41, s59
	s_mov_b32 m0, s41
	s_nop 0
	global_load_lds_dwordx4 v0, s[74:75]
	s_add_i32 m0, s41, 0x2000
	s_nop 0
	global_load_lds_dwordx4 v150, s[74:75]
	s_mov_b32 m0, s60
	s_nop 0
	global_load_lds_dwordx4 v146, s[54:55]
	s_mov_b32 m0, s61
	s_nop 0
	global_load_lds_dwordx4 v148, s[54:55]
	ds_read_b128 v[178:181], v169 offset:16384
	ds_read_b128 v[182:185], v169 offset:17408
	ds_read_b128 v[186:189], v169 offset:18432
	ds_read_b128 v[190:193], v169 offset:19456
	ds_read_b128 v[202:205], v169 offset:20480
	ds_read_b128 v[206:209], v169 offset:21504
	ds_read_b128 v[210:213], v169 offset:22528
	ds_read_b128 v[214:217], v169 offset:23552
	s_waitcnt vmcnt(8)
	s_waitcnt lgkmcnt(0)
	s_barrier
	s_setprio 1
	s_waitcnt lgkmcnt(0)
	v_mfma_f32_16x16x32_bf16 v[94:97], v[130:133], v[178:181], v[94:97]
	v_mfma_f32_16x16x32_bf16 v[90:93], v[138:141], v[178:181], v[90:93]
	v_mfma_f32_16x16x32_bf16 v[86:89], v[130:133], v[186:189], v[86:89]
	v_mfma_f32_16x16x32_bf16 v[82:85], v[138:141], v[186:189], v[82:85]
	v_mfma_f32_16x16x32_bf16 v[78:81], v[130:133], v[202:205], v[78:81]
	v_mfma_f32_16x16x32_bf16 v[74:77], v[138:141], v[202:205], v[74:77]
	v_mfma_f32_16x16x32_bf16 v[70:73], v[130:133], v[210:213], v[70:73]
	v_mfma_f32_16x16x32_bf16 v[66:69], v[138:141], v[210:213], v[66:69]
	v_mfma_f32_16x16x32_bf16 v[94:97], v[134:137], v[182:185], v[94:97]
	v_mfma_f32_16x16x32_bf16 v[90:93], v[142:145], v[182:185], v[90:93]
	v_mfma_f32_16x16x32_bf16 v[86:89], v[134:137], v[190:193], v[86:89]
	v_mfma_f32_16x16x32_bf16 v[82:85], v[142:145], v[190:193], v[82:85]
	v_mfma_f32_16x16x32_bf16 v[78:81], v[134:137], v[206:209], v[78:81]
	v_mfma_f32_16x16x32_bf16 v[74:77], v[142:145], v[206:209], v[74:77]
	v_mfma_f32_16x16x32_bf16 v[70:73], v[134:137], v[214:217], v[70:73]
	v_mfma_f32_16x16x32_bf16 v[66:69], v[142:145], v[214:217], v[66:69]
	s_setprio 0
	s_setprio 1
	v_mfma_f32_16x16x32_bf16 v[30:33], v[156:159], v[178:181], v[30:33]
	v_mfma_f32_16x16x32_bf16 v[26:29], v[170:173], v[178:181], v[26:29]
	v_mfma_f32_16x16x32_bf16 v[22:25], v[156:159], v[186:189], v[22:25]
	v_mfma_f32_16x16x32_bf16 v[18:21], v[170:173], v[186:189], v[18:21]
	v_mfma_f32_16x16x32_bf16 v[14:17], v[156:159], v[202:205], v[14:17]
	v_mfma_f32_16x16x32_bf16 v[10:13], v[170:173], v[202:205], v[10:13]
	v_mfma_f32_16x16x32_bf16 v[6:9], v[156:159], v[210:213], v[6:9]
	v_mfma_f32_16x16x32_bf16 v[2:5], v[170:173], v[210:213], v[2:5]
	v_mfma_f32_16x16x32_bf16 v[30:33], v[160:163], v[182:185], v[30:33]
	v_mfma_f32_16x16x32_bf16 v[26:29], v[174:177], v[182:185], v[26:29]
	v_mfma_f32_16x16x32_bf16 v[22:25], v[160:163], v[190:193], v[22:25]
	v_mfma_f32_16x16x32_bf16 v[18:21], v[174:177], v[190:193], v[18:21]
	v_mfma_f32_16x16x32_bf16 v[14:17], v[160:163], v[206:209], v[14:17]
	v_mfma_f32_16x16x32_bf16 v[10:13], v[174:177], v[206:209], v[10:13]
	v_mfma_f32_16x16x32_bf16 v[6:9], v[160:163], v[214:217], v[6:9]
	v_mfma_f32_16x16x32_bf16 v[2:5], v[174:177], v[214:217], v[2:5]
	s_setprio 0
	s_barrier
	s_add_u32 s98, s54, 0x40000
	s_addc_u32 s99, s55, 0
	s_mov_b32 m0, s62
	s_add_i32 s41, 0, 0x18000
	global_load_lds_dwordx4 v146, s[98:99]
	s_mov_b32 m0, s63
	s_add_i32 s49, 0, 0x1c000
	global_load_lds_dwordx4 v148, s[98:99]
	v_add_u32_e32 v142, s41, v168
	v_add_u32_e32 v174, s49, v168
	ds_read_b128 v[130:133], v142
	ds_read_b128 v[134:137], v142 offset:1024
	ds_read_b128 v[138:141], v142 offset:2048
	ds_read_b128 v[142:145], v142 offset:3072
	ds_read_b128 v[156:159], v174
	ds_read_b128 v[160:163], v174 offset:1024
	ds_read_b128 v[170:173], v174 offset:2048
	ds_read_b128 v[174:177], v174 offset:3072
	ds_read_b128 v[178:181], v169 offset:32768
	ds_read_b128 v[182:185], v169 offset:33792
	ds_read_b128 v[186:189], v169 offset:34816
	ds_read_b128 v[190:193], v169 offset:35840
	ds_read_b128 v[202:205], v169 offset:36864
	ds_read_b128 v[206:209], v169 offset:37888
	ds_read_b128 v[210:213], v169 offset:38912
	ds_read_b128 v[214:217], v169 offset:39936
	s_waitcnt vmcnt(8)
	s_waitcnt lgkmcnt(0)
	s_barrier
; #define PG8_STAGE(bufoff, gbase, voff) do { _Pragma("unroll") for (int _i = 0; _i < 2; ++_i) \
;         __builtin_amdgcn_global_load_lds((const unsigned*)((const char*)(gbase) + (voff)[_i]), (PG8_LAS unsigned*)(lds + (bufoff) + ldsw + _i * 8192), 16, 0, 0); } while (0)
; #define PG8_LDA(dst, b, h) do { _Pragma("unroll") for (int m = 0; m < 4; ++m) _Pragma("unroll") for (int k = 0; k < 2; ++k) dst[m][k] = *(const PG8_LAS bf16x8*)(lds + PG8_SA(b, h) + aoff + m * 2048 + k * 1024); } while (0)
; #define PG8_MMA(ai, bj, At, Bt) do { __builtin_amdgcn_s_setprio(1); _Pragma("unroll") for (int m = 0; m < 4; ++m) _Pragma("unroll") for (int n = 0; n < 2; ++n) _Pragma("unroll") for (int k = 0; k < 2; ++k) \
;         acc[ai][bj][m][n] = __builtin_amdgcn_mfma_f32_16x16x32_bf16(Bt[n][k], At[m][k], acc[ai][bj][m][n], 0, 0, 0); __builtin_amdgcn_s_setprio(0); } while (0)
; #define PG8_WAIT_V(n) asm volatile("s_waitcnt vmcnt(" #n ")" ::: "memory")
; #define PG8_WAIT_L(n) asm volatile("s_waitcnt lgkmcnt(" #n ")" ::: "memory")
; #define PG8_BAR __builtin_amdgcn_s_barrier()
; #define PG8_SCHED __builtin_amdgcn_sched_barrier(0)
; template <class Epi, class Sched>
; __device__ __forceinline__ void gemm_phase(PG8_LAS unsigned char* lds, const Gemm g, const Sched& S, const Epi& E) {
;     ...
;             PG8_WAIT_V(8); PG8_WAIT_L(0); PG8_BAR; PG8_MMA(0, 0, At, B0); PG8_MMA(0, 1, At, B1); PG8_BAR; PG8_SCHED;
;             PG8_LDA(At, 1, 1); PG8_STAGE(PG8_SB(1, 0), b3, voffB); PG8_STAGE(PG8_SB(1, 1), b3 + hstepB, voffB); PG8_STAGE(PG8_SA(1, 0), a3, voffA);
;             PG8_WAIT_V(8); PG8_WAIT_L(0); PG8_BAR; PG8_MMA(1, 0, At, B0); PG8_MMA(1, 1, At, B1); PG8_BAR; PG8_SCHED;
;         }
;         if (wr == 0) PG8_BAR;
	s_setprio 1
	s_waitcnt lgkmcnt(0)
	v_mfma_f32_16x16x32_bf16 v[126:129], v[130:133], v[178:181], v[126:129]
	v_mfma_f32_16x16x32_bf16 v[122:125], v[138:141], v[178:181], v[122:125]
	v_mfma_f32_16x16x32_bf16 v[118:121], v[130:133], v[186:189], v[118:121]
	v_mfma_f32_16x16x32_bf16 v[114:117], v[138:141], v[186:189], v[114:117]
	v_mfma_f32_16x16x32_bf16 v[110:113], v[130:133], v[202:205], v[110:113]
	v_mfma_f32_16x16x32_bf16 v[106:109], v[138:141], v[202:205], v[106:109]
	v_mfma_f32_16x16x32_bf16 v[102:105], v[130:133], v[210:213], v[102:105]
	v_mfma_f32_16x16x32_bf16 v[98:101], v[138:141], v[210:213], v[98:101]
	v_mfma_f32_16x16x32_bf16 v[126:129], v[134:137], v[182:185], v[126:129]
	v_mfma_f32_16x16x32_bf16 v[122:125], v[142:145], v[182:185], v[122:125]
	v_mfma_f32_16x16x32_bf16 v[118:121], v[134:137], v[190:193], v[118:121]
	v_mfma_f32_16x16x32_bf16 v[114:117], v[142:145], v[190:193], v[114:117]
	v_mfma_f32_16x16x32_bf16 v[110:113], v[134:137], v[206:209], v[110:113]
	v_mfma_f32_16x16x32_bf16 v[106:109], v[142:145], v[206:209], v[106:109]
	v_mfma_f32_16x16x32_bf16 v[102:105], v[134:137], v[214:217], v[102:105]
	v_mfma_f32_16x16x32_bf16 v[98:101], v[142:145], v[214:217], v[98:101]
	s_setprio 0
	s_setprio 1
	v_mfma_f32_16x16x32_bf16 v[62:65], v[156:159], v[178:181], v[62:65]
	v_mfma_f32_16x16x32_bf16 v[58:61], v[170:173], v[178:181], v[58:61]
	v_mfma_f32_16x16x32_bf16 v[54:57], v[156:159], v[186:189], v[54:57]
	v_mfma_f32_16x16x32_bf16 v[50:53], v[170:173], v[186:189], v[50:53]
	v_mfma_f32_16x16x32_bf16 v[46:49], v[156:159], v[202:205], v[46:49]
	v_mfma_f32_16x16x32_bf16 v[42:45], v[170:173], v[202:205], v[42:45]
	v_mfma_f32_16x16x32_bf16 v[38:41], v[156:159], v[210:213], v[38:41]
	v_mfma_f32_16x16x32_bf16 v[34:37], v[170:173], v[210:213], v[34:37]
	v_mfma_f32_16x16x32_bf16 v[62:65], v[160:163], v[182:185], v[62:65]
	v_mfma_f32_16x16x32_bf16 v[58:61], v[174:177], v[182:185], v[58:61]
	v_mfma_f32_16x16x32_bf16 v[54:57], v[160:163], v[190:193], v[54:57]
	v_mfma_f32_16x16x32_bf16 v[50:53], v[174:177], v[190:193], v[50:53]
	v_mfma_f32_16x16x32_bf16 v[46:49], v[160:163], v[206:209], v[46:49]
	v_mfma_f32_16x16x32_bf16 v[42:45], v[174:177], v[206:209], v[42:45]
	v_mfma_f32_16x16x32_bf16 v[38:41], v[160:163], v[214:217], v[38:41]
	v_mfma_f32_16x16x32_bf16 v[34:37], v[174:177], v[214:217], v[34:37]
	s_setprio 0
	s_barrier
	s_add_i32 s41, s41, s59
	s_add_i32 m0, s41, 0xffffff80
	s_nop 0
	global_load_lds_dwordx4 v0, s[52:53] offset:128
	s_add_i32 m0, s41, 0x1f80
	s_add_i32 s41, s49, s59
	global_load_lds_dwordx4 v150, s[52:53] offset:128
	s_add_i32 m0, s41, 0xffffff80
	s_nop 0
	global_load_lds_dwordx4 v0, s[74:75] offset:128
	s_add_i32 m0, s41, 0x1f80
	s_nop 0
	global_load_lds_dwordx4 v150, s[74:75] offset:128
	s_add_i32 m0, s66, 0xffffff80
	s_nop 0
	global_load_lds_dwordx4 v146, s[54:55] offset:128
	s_add_i32 m0, s67, 0xffffff80
	s_nop 0
	global_load_lds_dwordx4 v148, s[54:55] offset:128
	ds_read_b128 v[178:181], v169 offset:49152
	ds_read_b128 v[182:185], v169 offset:50176
	ds_read_b128 v[186:189], v169 offset:51200
	ds_read_b128 v[190:193], v169 offset:52224
	ds_read_b128 v[202:205], v169 offset:53248
	ds_read_b128 v[206:209], v169 offset:54272
	ds_read_b128 v[210:213], v169 offset:55296
	ds_read_b128 v[214:217], v169 offset:56320
	s_waitcnt vmcnt(8)
	s_waitcnt lgkmcnt(0)
	s_barrier
	s_setprio 1
	s_waitcnt lgkmcnt(0)
	v_mfma_f32_16x16x32_bf16 v[94:97], v[130:133], v[178:181], v[94:97]
	v_mfma_f32_16x16x32_bf16 v[90:93], v[138:141], v[178:181], v[90:93]
	v_mfma_f32_16x16x32_bf16 v[86:89], v[130:133], v[186:189], v[86:89]
	v_mfma_f32_16x16x32_bf16 v[82:85], v[138:141], v[186:189], v[82:85]
	v_mfma_f32_16x16x32_bf16 v[78:81], v[130:133], v[202:205], v[78:81]
	v_mfma_f32_16x16x32_bf16 v[74:77], v[138:141], v[202:205], v[74:77]
	v_mfma_f32_16x16x32_bf16 v[70:73], v[130:133], v[210:213], v[70:73]
	v_mfma_f32_16x16x32_bf16 v[66:69], v[138:141], v[210:213], v[66:69]
	v_mfma_f32_16x16x32_bf16 v[94:97], v[134:137], v[182:185], v[94:97]
	v_mfma_f32_16x16x32_bf16 v[90:93], v[142:145], v[182:185], v[90:93]
	v_mfma_f32_16x16x32_bf16 v[86:89], v[134:137], v[190:193], v[86:89]
	v_mfma_f32_16x16x32_bf16 v[82:85], v[142:145], v[190:193], v[82:85]
	v_mfma_f32_16x16x32_bf16 v[78:81], v[134:137], v[206:209], v[78:81]
	v_mfma_f32_16x16x32_bf16 v[74:77], v[142:145], v[206:209], v[74:77]
	v_mfma_f32_16x16x32_bf16 v[70:73], v[134:137], v[214:217], v[70:73]
	v_mfma_f32_16x16x32_bf16 v[66:69], v[142:145], v[214:217], v[66:69]
	s_setprio 0
	s_setprio 1
	v_mfma_f32_16x16x32_bf16 v[30:33], v[156:159], v[178:181], v[30:33]
	v_mfma_f32_16x16x32_bf16 v[26:29], v[170:173], v[178:181], v[26:29]
	v_mfma_f32_16x16x32_bf16 v[22:25], v[156:159], v[186:189], v[22:25]
	v_mfma_f32_16x16x32_bf16 v[18:21], v[170:173], v[186:189], v[18:21]
	v_mfma_f32_16x16x32_bf16 v[14:17], v[156:159], v[202:205], v[14:17]
	v_mfma_f32_16x16x32_bf16 v[10:13], v[170:173], v[202:205], v[10:13]
	v_mfma_f32_16x16x32_bf16 v[6:9], v[156:159], v[210:213], v[6:9]
	v_mfma_f32_16x16x32_bf16 v[2:5], v[170:173], v[210:213], v[2:5]
	v_mfma_f32_16x16x32_bf16 v[30:33], v[160:163], v[182:185], v[30:33]
	v_mfma_f32_16x16x32_bf16 v[26:29], v[174:177], v[182:185], v[26:29]
	v_mfma_f32_16x16x32_bf16 v[22:25], v[160:163], v[190:193], v[22:25]
	v_mfma_f32_16x16x32_bf16 v[18:21], v[174:177], v[190:193], v[18:21]
	v_mfma_f32_16x16x32_bf16 v[14:17], v[160:163], v[206:209], v[14:17]
	v_mfma_f32_16x16x32_bf16 v[10:13], v[174:177], v[206:209], v[10:13]
	v_mfma_f32_16x16x32_bf16 v[6:9], v[160:163], v[214:217], v[6:9]
	v_mfma_f32_16x16x32_bf16 v[2:5], v[174:177], v[214:217], v[2:5]
	s_setprio 0
	s_barrier
	s_add_i32 s39, s39, 2
	s_add_u32 s6, s6, 0x100
	s_addc_u32 s7, s7, 0
	s_add_u32 s2, s2, 0x100
	s_addc_u32 s18, s18, 0
	s_cmp_gt_u32 s39, 13
	s_cbranch_scc0 .LBB0_161
	s_and_b64 vcc, exec, s[14:15]
	s_cbranch_vccz .LBB0_164
	s_barrier
